# strip operands staged via wave-private LDS-DMA ring (coalesced 64B/row) instead of direct MFMA-layout global loads
# speedup vs baseline: 1.0495x; 1.0495x over previous
;     __device__ __forceinline__ void mid(f32x4 (&acc)[2][2][4][2], const pg8::Unit& u, int wr, int wc, int fr, int fq) const {
; #pragma unroll
;         for (int ai = 0; ai < 2; ++ai)
; #pragma unroll
;             for (int m = 0; m < 4; ++m) { const int row = u.pm * 256 + ai * 128 + wr * 64 + m * 16 + fr;
; #pragma unroll
;                 for (int bj = 0; bj < 2; ++bj) { const int col = u.pn * 256 + bj * 128 + wc * 32 + 8 * fq; const bf16_t* gp = G + (size_t)row * 2048 + col;
;                     f32x4 l0, l1, a0, a1; unpack_bf16x8(*(const u32x4*)gp, l0, l1); unpack_bf16x8(*(const u32x4*)(gp + 1024), a0, a1);
; #pragma unroll
;                     for (int i = 0; i < 4; ++i) { acc[ai][bj][m][0][i] *= l0[i] * __builtin_amdgcn_rcpf(fmaxf(a0[i], 1e-30f)); acc[ai][bj][m][1][i] *= l1[i] * __builtin_amdgcn_rcpf(fmaxf(a1[i], 1e-30f)); } } }
.LBB0_674:
	s_waitcnt vmcnt(0)
	v_readlane_b32 s46, v254, 22
	s_barrier
	s_and_b32 s0, s44, 7
	s_lshr_b32 s1, s44, 3
	s_and_b32 s1, s1, 7
	s_lshl_b32 s0, s0, 3
	s_add_i32 s0, s0, s1
	s_mulk_i32 s0, 0x110
	s_addk_i32 s0, 0x100
	s_lshr_b32 s1, s44, 6
	v_readlane_b32 s2, v254, 21
	s_nop 3
	s_lshl_b32 s3, s1, 8
	s_mul_i32 s21, s2, 15360
	s_lshl_b32 s2, s2, 5
	s_add_i32 s3, s3, s2
	s_mov_b32 s4, 0x1000
	s_add_u32 s8, s88, 0x14000000
	s_addc_u32 s9, s89, 0
	s_add_u32 s10, s88, 0x1600000
	s_addc_u32 s11, s89, 0
	s_mov_b64 s[6:7], 0x4000
	s_mov_b64 s[12:13], 64
	v_and_b32_e32 v8, 15, v132
	v_lshrrev_b32_e32 v9, 4, v132
	v_add_u32_e32 v5, s0, v8
	v_lshl_add_u32 v2, v9, 3, s3
	v_lshlrev_b32_e32 v6, 4, v9
	v_lshrrev_b32_e32 v7, 3, v8
	v_lshlrev_b32_e32 v7, 5, v7
	v_xor_b32_e32 v6, v6, v7
	v_lshl_add_u32 v6, v8, 6, v6
	v_add_u32_e32 v6, s21, v6
	v_lshrrev_b32_e32 v36, 2, v132
	v_and_b32_e32 v37, 3, v132
	v_lshrrev_b32_e32 v38, 5, v132
	v_lshlrev_b32_e32 v37, 4, v37
	v_lshlrev_b32_e32 v38, 5, v38
	v_xor_b32_e32 v37, v37, v38
	v_add_u32_e32 v38, s0, v36
	v_lshrrev_b32_e32 v39, 2, v36
	v_and_b32_e32 v40, 3, v36
	v_lshl_add_u32 v39, v39, 3, v40
	v_add_u32_e32 v39, s3, v39
	v_mul_lo_u32 v10, v38, s4
	v_mul_lo_u32 v12, v39, s4
	v_mov_b32_e32 v11, 0
	v_mov_b32_e32 v13, 0
	v_add_u32_e32 v10, v10, v37
	v_add_u32_e32 v12, v12, v37
	v_lshl_add_u64 v[10:11], s[8:9], 0, v[10:11]
	v_lshl_add_u64 v[12:13], s[10:11], 0, v[12:13]
	v_lshl_add_u64 v[14:15], v[12:13], 0, s[6:7]
	s_add_u32 s22, s88, 0xfc00000
	s_addc_u32 s23, s89, 0
	v_lshlrev_b32_e32 v0, 12, v5
	v_lshl_add_u32 v0, v2, 1, v0
	v_mov_b32_e32 v1, 0
	v_lshl_add_u64 v[0:1], s[22:23], 0, v[0:1]
	global_load_dwordx4 v[120:123], v[0:1], off
	global_load_dwordx4 v[124:127], v[0:1], off offset:2048
	v_mov_b32_e32 v16, 0
	v_mov_b32_e32 v17, 0
	v_mov_b32_e32 v18, 0
	v_mov_b32_e32 v19, 0
	v_mov_b32_e32 v20, 0
	v_mov_b32_e32 v21, 0
	v_mov_b32_e32 v22, 0
	v_mov_b32_e32 v23, 0
	s_mov_b32 s22, s21
	s_mov_b32 m0, s22
	s_nop 0
	global_load_lds_dwordx4 v[10:11], off
	s_add_i32 m0, s22, 1024
	s_nop 0
	global_load_lds_dwordx4 v[12:13], off
	s_add_i32 m0, s22, 2048
	s_nop 0
	global_load_lds_dwordx4 v[14:15], off
	v_lshl_add_u64 v[10:11], v[10:11], 0, s[12:13]
	v_lshl_add_u64 v[12:13], v[12:13], 0, s[12:13]
	v_lshl_add_u64 v[14:15], v[14:15], 0, s[12:13]
	s_addk_i32 s22, 3072
	s_mov_b32 m0, s22
	s_nop 0
	global_load_lds_dwordx4 v[10:11], off
	s_add_i32 m0, s22, 1024
	s_nop 0
	global_load_lds_dwordx4 v[12:13], off
	s_add_i32 m0, s22, 2048
	s_nop 0
	global_load_lds_dwordx4 v[14:15], off
	v_lshl_add_u64 v[10:11], v[10:11], 0, s[12:13]
	v_lshl_add_u64 v[12:13], v[12:13], 0, s[12:13]
	v_lshl_add_u64 v[14:15], v[14:15], 0, s[12:13]
	s_addk_i32 s22, 3072
	s_mov_b32 m0, s22
	s_nop 0
	global_load_lds_dwordx4 v[10:11], off
	s_add_i32 m0, s22, 1024
	s_nop 0
	global_load_lds_dwordx4 v[12:13], off
	s_add_i32 m0, s22, 2048
	s_nop 0
	global_load_lds_dwordx4 v[14:15], off
	v_lshl_add_u64 v[10:11], v[10:11], 0, s[12:13]
	v_lshl_add_u64 v[12:13], v[12:13], 0, s[12:13]
	v_lshl_add_u64 v[14:15], v[14:15], 0, s[12:13]
	s_addk_i32 s22, 3072
	s_mov_b32 m0, s22
	s_nop 0
	global_load_lds_dwordx4 v[10:11], off
	s_add_i32 m0, s22, 1024
	s_nop 0
	global_load_lds_dwordx4 v[12:13], off
	s_add_i32 m0, s22, 2048
	s_nop 0
	global_load_lds_dwordx4 v[14:15], off
	v_lshl_add_u64 v[10:11], v[10:11], 0, s[12:13]
	v_lshl_add_u64 v[12:13], v[12:13], 0, s[12:13]
	v_lshl_add_u64 v[14:15], v[14:15], 0, s[12:13]
	s_addk_i32 s22, 3072
	s_mov_b32 m0, s22
	s_nop 0
	global_load_lds_dwordx4 v[10:11], off
	s_add_i32 m0, s22, 1024
	s_nop 0
	global_load_lds_dwordx4 v[12:13], off
	s_add_i32 m0, s22, 2048
	s_nop 0
	global_load_lds_dwordx4 v[14:15], off
	v_lshl_add_u64 v[10:11], v[10:11], 0, s[12:13]
	v_lshl_add_u64 v[12:13], v[12:13], 0, s[12:13]
	v_lshl_add_u64 v[14:15], v[14:15], 0, s[12:13]
	s_mov_b32 s20, 0
	s_mov_b32 s5, 32
; __device__ __forceinline__ u32x4 pack8(f32x4 a, f32x4 b) { u32x4 w; w.x = cvt_pk_bf16(a[0], a[1]); w.y = cvt_pk_bf16(a[2], a[3]); w.z = cvt_pk_bf16(b[0], b[1]); w.w = cvt_pk_bf16(b[2], b[3]); return w; }
; #define EPI_LOOP(...) _Pragma("unroll") for (int ai = 0; ai < 2; ++ai) _Pragma("unroll") for (int m = 0; m < 4; ++m) { const int row = u.pm * 256 + ai * 128 + wr * 64 + m * 16 + fr; \
;     _Pragma("unroll") for (int bj = 0; bj < 2; ++bj) { const int tc = bj * 128 + wc * 32 + 8 * fq; f32x4 v0 = acc[ai][bj][m][0], v1 = acc[ai][bj][m][1]; __VA_ARGS__ } }
;     __device__ __forceinline__ void mid(f32x4 (&acc)[2][2][4][2], const pg8::Unit& u, int wr, int wc, int fr, int fq) const {
; #pragma unroll
;         for (int ai = 0; ai < 2; ++ai)
; #pragma unroll
;             for (int m = 0; m < 4; ++m) { const int row = u.pm * 256 + ai * 128 + wr * 64 + m * 16 + fr;
; #pragma unroll
;                 for (int bj = 0; bj < 2; ++bj) { const int col = u.pn * 256 + bj * 128 + wc * 32 + 8 * fq; const bf16_t* gp = G + (size_t)row * 2048 + col;
;                     f32x4 l0, l1, a0, a1; unpack_bf16x8(*(const u32x4*)gp, l0, l1); unpack_bf16x8(*(const u32x4*)(gp + 1024), a0, a1);
; #pragma unroll
;                     for (int i = 0; i < 4; ++i) { acc[ai][bj][m][0][i] *= l0[i] * __builtin_amdgcn_rcpf(fmaxf(a0[i], 1e-30f)); acc[ai][bj][m][1][i] *= l1[i] * __builtin_amdgcn_rcpf(fmaxf(a1[i], 1e-30f)); } } }
;     }
;     __device__ __forceinline__ void operator()(const f32x4 (&acc)[2][2][4][2], const pg8::Unit& u, int wr, int wc, int fr, int fq) const {
;         EPI_LOOP({ const int col = u.pn * 256 + tc; f32x4 a0, a1; unpack_bf16x8(*(const u32x4*)(G + (size_t)row * 2048 + 1024 + col), a0, a1);
;                    _Pragma("unroll") for (int i = 0; i < 4; ++i) { a0[i] = fmaxf(a0[i], 1e-30f); a1[i] = fmaxf(a1[i], 1e-30f); }
;                    *(u32x4*)(MIXED + (size_t)row * D + col) = pack8(v0 * a0, v1 * a1); })
;     }
.Lstrip_P3_k1:
	s_waitcnt vmcnt(12)
	v_add_u32_e32 v7, s20, v6
	ds_read_b128 v[24:27], v7
	ds_read_b128 v[28:31], v7 offset:1024
	ds_read_b128 v[32:35], v7 offset:2048
	s_add_i32 s22, s21, s20
	s_waitcnt lgkmcnt(0)
	s_mov_b32 m0, s22
	s_nop 0
	global_load_lds_dwordx4 v[10:11], off
	s_add_i32 m0, s22, 1024
	s_nop 0
	global_load_lds_dwordx4 v[12:13], off
	s_add_i32 m0, s22, 2048
	s_nop 0
	global_load_lds_dwordx4 v[14:15], off
	v_lshl_add_u64 v[10:11], v[10:11], 0, s[12:13]
	v_lshl_add_u64 v[12:13], v[12:13], 0, s[12:13]
	v_lshl_add_u64 v[14:15], v[14:15], 0, s[12:13]
	v_mfma_f32_16x16x32_bf16 v[16:19], v[28:31], v[24:27], v[16:19]
	v_mfma_f32_16x16x32_bf16 v[20:23], v[32:35], v[24:27], v[20:23]
	s_addk_i32 s20, 3072
	s_cmpk_eq_u32 s20, 15360
	s_cselect_b32 s20, 0, s20
	s_add_i32 s5, s5, -1
	s_cmp_lg_u32 s5, 0
	s_cbranch_scc1 .Lstrip_P3_k1
	s_nop 7
	s_nop 1
	v_lshlrev_b32_e32 v136, 16, v120
	v_and_b32_e32 v137, 0xffff0000, v120
	v_lshlrev_b32_e32 v138, 16, v121
	v_and_b32_e32 v139, 0xffff0000, v121
	v_lshlrev_b32_e32 v140, 16, v122
	v_and_b32_e32 v141, 0xffff0000, v122
	v_lshlrev_b32_e32 v142, 16, v123
	v_and_b32_e32 v143, 0xffff0000, v123
	v_lshlrev_b32_e32 v144, 16, v124
	v_and_b32_e32 v145, 0xffff0000, v124
	v_lshlrev_b32_e32 v146, 16, v125
	v_and_b32_e32 v147, 0xffff0000, v125
	v_lshlrev_b32_e32 v148, 16, v126
	v_and_b32_e32 v149, 0xffff0000, v126
	v_lshlrev_b32_e32 v150, 16, v127
	v_and_b32_e32 v151, 0xffff0000, v127
	v_max_f32_e32 v144, 0xda24260, v144
	v_max_f32_e32 v145, 0xda24260, v145
	v_max_f32_e32 v146, 0xda24260, v146
	v_max_f32_e32 v147, 0xda24260, v147
	v_max_f32_e32 v148, 0xda24260, v148
	v_max_f32_e32 v149, 0xda24260, v149
	v_max_f32_e32 v150, 0xda24260, v150
	v_max_f32_e32 v151, 0xda24260, v151
	v_rcp_f32_e32 v152, v144
	v_rcp_f32_e32 v153, v145
	v_rcp_f32_e32 v154, v146
	v_rcp_f32_e32 v155, v147
	v_rcp_f32_e32 v156, v148
	v_rcp_f32_e32 v157, v149
	v_rcp_f32_e32 v158, v150
	v_rcp_f32_e32 v159, v151
	s_nop 0
	v_mul_f32_e32 v136, v152, v136
	v_mul_f32_e32 v137, v153, v137
	v_mul_f32_e32 v138, v154, v138
	v_mul_f32_e32 v139, v155, v139
	v_mul_f32_e32 v140, v156, v140
	v_mul_f32_e32 v141, v157, v141
	v_mul_f32_e32 v142, v158, v142
	v_mul_f32_e32 v143, v159, v143
	v_mul_f32_e32 v16, v16, v136
	v_mul_f32_e32 v17, v17, v137
	v_mul_f32_e32 v18, v18, v138
	v_mul_f32_e32 v19, v19, v139
	v_mul_f32_e32 v20, v20, v140
	v_mul_f32_e32 v21, v21, v141
	v_mul_f32_e32 v22, v22, v142
	v_mul_f32_e32 v23, v23, v143
	s_nop 1
	s_mov_b32 s5, 27
.Lstrip_P3_k2:
	s_waitcnt vmcnt(12)
	v_add_u32_e32 v7, s20, v6
	ds_read_b128 v[24:27], v7
	ds_read_b128 v[28:31], v7 offset:1024
	ds_read_b128 v[32:35], v7 offset:2048
	s_add_i32 s22, s21, s20
	s_waitcnt lgkmcnt(0)
	s_mov_b32 m0, s22
	s_nop 0
	global_load_lds_dwordx4 v[10:11], off
	s_add_i32 m0, s22, 1024
	s_nop 0
	global_load_lds_dwordx4 v[12:13], off
	s_add_i32 m0, s22, 2048
	s_nop 0
	global_load_lds_dwordx4 v[14:15], off
	v_lshl_add_u64 v[10:11], v[10:11], 0, s[12:13]
	v_lshl_add_u64 v[12:13], v[12:13], 0, s[12:13]
	v_lshl_add_u64 v[14:15], v[14:15], 0, s[12:13]
	v_mfma_f32_16x16x32_bf16 v[16:19], v[28:31], v[24:27], v[16:19]
	v_mfma_f32_16x16x32_bf16 v[20:23], v[32:35], v[24:27], v[20:23]
	s_addk_i32 s20, 3072
	s_cmpk_eq_u32 s20, 15360
	s_cselect_b32 s20, 0, s20
	s_add_i32 s5, s5, -1
	s_cmp_lg_u32 s5, 0
	s_cbranch_scc1 .Lstrip_P3_k2
	s_waitcnt vmcnt(12)
	ds_read_b128 v[24:27], v6 offset:12288
	ds_read_b128 v[28:31], v6 offset:13312
	ds_read_b128 v[32:35], v6 offset:14336
	s_waitcnt lgkmcnt(0)
	v_mfma_f32_16x16x32_bf16 v[16:19], v[28:31], v[24:27], v[16:19]
	v_mfma_f32_16x16x32_bf16 v[20:23], v[32:35], v[24:27], v[20:23]
	s_waitcnt vmcnt(9)
	ds_read_b128 v[24:27], v6 offset:0
	ds_read_b128 v[28:31], v6 offset:1024
	ds_read_b128 v[32:35], v6 offset:2048
	s_waitcnt lgkmcnt(0)
	v_mfma_f32_16x16x32_bf16 v[16:19], v[28:31], v[24:27], v[16:19]
	v_mfma_f32_16x16x32_bf16 v[20:23], v[32:35], v[24:27], v[20:23]
	s_waitcnt vmcnt(6)
	ds_read_b128 v[24:27], v6 offset:3072
	ds_read_b128 v[28:31], v6 offset:4096
	ds_read_b128 v[32:35], v6 offset:5120
	s_waitcnt lgkmcnt(0)
	v_mfma_f32_16x16x32_bf16 v[16:19], v[28:31], v[24:27], v[16:19]
	v_mfma_f32_16x16x32_bf16 v[20:23], v[32:35], v[24:27], v[20:23]
	s_waitcnt vmcnt(3)
	ds_read_b128 v[24:27], v6 offset:6144
	ds_read_b128 v[28:31], v6 offset:7168
	ds_read_b128 v[32:35], v6 offset:8192
	s_waitcnt lgkmcnt(0)
	v_mfma_f32_16x16x32_bf16 v[16:19], v[28:31], v[24:27], v[16:19]
	v_mfma_f32_16x16x32_bf16 v[20:23], v[32:35], v[24:27], v[20:23]
	s_waitcnt vmcnt(0)
	ds_read_b128 v[24:27], v6 offset:9216
	ds_read_b128 v[28:31], v6 offset:10240
	ds_read_b128 v[32:35], v6 offset:11264
	s_waitcnt lgkmcnt(0)
	v_mfma_f32_16x16x32_bf16 v[16:19], v[28:31], v[24:27], v[16:19]
	v_mfma_f32_16x16x32_bf16 v[20:23], v[32:35], v[24:27], v[20:23]
	s_nop 7
	s_nop 1
	v_mul_f32_e32 v16, v16, v144
	v_mul_f32_e32 v17, v17, v145
	v_mul_f32_e32 v18, v18, v146
	v_mul_f32_e32 v19, v19, v147
	v_mul_f32_e32 v20, v20, v148
	v_mul_f32_e32 v21, v21, v149
	v_mul_f32_e32 v22, v22, v150
	v_mul_f32_e32 v23, v23, v151
	v_cvt_pk_bf16_f32 v136, v16, v17
	v_cvt_pk_bf16_f32 v137, v18, v19
	v_cvt_pk_bf16_f32 v138, v20, v21
	v_cvt_pk_bf16_f32 v139, v22, v23
	s_add_u32 s22, s88, 0x3000000
	s_addc_u32 s23, s89, 0
	v_lshlrev_b32_e32 v0, 11, v5
	v_lshl_add_u32 v0, v2, 1, v0
	v_mov_b32_e32 v1, 0
	v_lshl_add_u64 v[0:1], s[22:23], 0, v[0:1]
	global_store_dwordx4 v[0:1], v[136:139], off

; __device__ __forceinline__ u32x4 pack8(f32x4 a, f32x4 b) { u32x4 w; w.x = cvt_pk_bf16(a[0], a[1]); w.y = cvt_pk_bf16(a[2], a[3]); w.z = cvt_pk_bf16(b[0], b[1]); w.w = cvt_pk_bf16(b[2], b[3]); return w; }
;     __device__ __forceinline__ void operator()(const f32x4 (&acc)[2][2][4][2], const pg8::Unit& u, int wr, int wc, int fr, int fq) const {
;     ...
;             for (int m = 0; m < 4; ++m) { const int row = u.pm * 256 + ai * 128 + wr * 64 + m * 16 + fr; float ss = 0.f;
;                 const float* xrow = row < MP ? xp + (size_t)row * D : xs + (size_t)(row - MP) * D;
; #pragma unroll
;                 for (int bj = 0; bj < 2; ++bj) { const int col = u.pn * 256 + bj * 128 + wc * 32 + 8 * fq;
;                     f32x4 v0 = acc[ai][bj][m][0] + *(const f32x4*)(xrow + col), v1 = acc[ai][bj][m][1] + *(const f32x4*)(xrow + col + 4);
;                     ss += (v0[0] * v0[0] + v0[1] * v0[1]) + (v0[2] * v0[2] + v0[3] * v0[3]) + (v1[0] * v1[0] + v1[1] * v1[1]) + (v1[2] * v1[2] + v1[3] * v1[3]);
;                     *(u32x4*)(X2B + (size_t)row * D + col) = pack8(v0, v1); }
.LBB0_793:
	s_waitcnt vmcnt(0)
	v_readlane_b32 s46, v254, 22
	s_barrier
	s_and_b32 s0, s44, 7
	s_lshr_b32 s1, s44, 3
	s_and_b32 s1, s1, 7
	s_lshl_b32 s0, s0, 3
	s_add_i32 s0, s0, s1
	s_mulk_i32 s0, 0x110
	s_addk_i32 s0, 0x100
	s_lshr_b32 s1, s44, 6
	v_readlane_b32 s2, v254, 21
	s_nop 3
	s_lshl_b32 s3, s1, 8
	s_mul_i32 s21, s2, 15360
	s_lshl_b32 s2, s2, 5
	s_add_i32 s3, s3, s2
	s_mov_b32 s4, 0x800
	s_add_u32 s8, s88, 0x3000000
	s_addc_u32 s9, s89, 0
	s_add_u32 s10, s88, 0x1a00000
	s_addc_u32 s11, s89, 0
	s_mov_b64 s[6:7], 0x2000
	s_mov_b64 s[12:13], 64
	v_and_b32_e32 v8, 15, v132
	v_lshrrev_b32_e32 v9, 4, v132
	v_add_u32_e32 v5, s0, v8
	v_lshl_add_u32 v2, v9, 3, s3
	v_lshlrev_b32_e32 v6, 4, v9
	v_lshrrev_b32_e32 v7, 3, v8
	v_lshlrev_b32_e32 v7, 5, v7
	v_xor_b32_e32 v6, v6, v7
	v_lshl_add_u32 v6, v8, 6, v6
	v_add_u32_e32 v6, s21, v6
	v_lshrrev_b32_e32 v36, 2, v132
	v_and_b32_e32 v37, 3, v132
	v_lshrrev_b32_e32 v38, 5, v132
	v_lshlrev_b32_e32 v37, 4, v37
	v_lshlrev_b32_e32 v38, 5, v38
	v_xor_b32_e32 v37, v37, v38
	v_add_u32_e32 v38, s0, v36
	v_lshrrev_b32_e32 v39, 2, v36
	v_and_b32_e32 v40, 3, v36
	v_lshl_add_u32 v39, v39, 3, v40
	v_add_u32_e32 v39, s3, v39
	v_mul_lo_u32 v10, v38, s4
	v_mul_lo_u32 v12, v39, s4
	v_mov_b32_e32 v11, 0
	v_mov_b32_e32 v13, 0
	v_add_u32_e32 v10, v10, v37
	v_add_u32_e32 v12, v12, v37
	v_lshl_add_u64 v[10:11], s[8:9], 0, v[10:11]
	v_lshl_add_u64 v[12:13], s[10:11], 0, v[12:13]
	v_lshl_add_u64 v[14:15], v[12:13], 0, s[6:7]
	s_cmp_lt_u32 s0, 0x4000
	s_cselect_b32 s22, s52, s54
	s_cselect_b32 s23, s53, s55
	s_cselect_b32 s20, 0, 0x4000
	v_subrev_u32_e32 v0, s20, v5
	v_lshlrev_b32_e32 v0, 12, v0
	v_lshl_add_u32 v0, v2, 2, v0
	v_mov_b32_e32 v1, 0
	v_lshl_add_u64 v[0:1], s[22:23], 0, v[0:1]
	global_load_dwordx4 v[120:123], v[0:1], off
	global_load_dwordx4 v[124:127], v[0:1], off offset:16
	v_mov_b32_e32 v16, 0
	v_mov_b32_e32 v17, 0
	v_mov_b32_e32 v18, 0
	v_mov_b32_e32 v19, 0
	v_mov_b32_e32 v20, 0
	v_mov_b32_e32 v21, 0
	v_mov_b32_e32 v22, 0
	v_mov_b32_e32 v23, 0
	s_mov_b32 s22, s21
	s_mov_b32 m0, s22
	s_nop 0
	global_load_lds_dwordx4 v[10:11], off
	s_add_i32 m0, s22, 1024
	s_nop 0
	global_load_lds_dwordx4 v[12:13], off
	s_add_i32 m0, s22, 2048
	s_nop 0
	global_load_lds_dwordx4 v[14:15], off
	v_lshl_add_u64 v[10:11], v[10:11], 0, s[12:13]
	v_lshl_add_u64 v[12:13], v[12:13], 0, s[12:13]
	v_lshl_add_u64 v[14:15], v[14:15], 0, s[12:13]
	s_addk_i32 s22, 3072
	s_mov_b32 m0, s22
	s_nop 0
	global_load_lds_dwordx4 v[10:11], off
	s_add_i32 m0, s22, 1024
	s_nop 0
	global_load_lds_dwordx4 v[12:13], off
	s_add_i32 m0, s22, 2048
	s_nop 0
	global_load_lds_dwordx4 v[14:15], off
	v_lshl_add_u64 v[10:11], v[10:11], 0, s[12:13]
	v_lshl_add_u64 v[12:13], v[12:13], 0, s[12:13]
	v_lshl_add_u64 v[14:15], v[14:15], 0, s[12:13]
	s_addk_i32 s22, 3072
	s_mov_b32 m0, s22
	s_nop 0
	global_load_lds_dwordx4 v[10:11], off
	s_add_i32 m0, s22, 1024
	s_nop 0
	global_load_lds_dwordx4 v[12:13], off
	s_add_i32 m0, s22, 2048
	s_nop 0
	global_load_lds_dwordx4 v[14:15], off
	v_lshl_add_u64 v[10:11], v[10:11], 0, s[12:13]
	v_lshl_add_u64 v[12:13], v[12:13], 0, s[12:13]
	v_lshl_add_u64 v[14:15], v[14:15], 0, s[12:13]
	s_addk_i32 s22, 3072
	s_mov_b32 m0, s22
	s_nop 0
	global_load_lds_dwordx4 v[10:11], off
	s_add_i32 m0, s22, 1024
	s_nop 0
	global_load_lds_dwordx4 v[12:13], off
	s_add_i32 m0, s22, 2048
	s_nop 0
	global_load_lds_dwordx4 v[14:15], off
	v_lshl_add_u64 v[10:11], v[10:11], 0, s[12:13]
	v_lshl_add_u64 v[12:13], v[12:13], 0, s[12:13]
	v_lshl_add_u64 v[14:15], v[14:15], 0, s[12:13]
	s_addk_i32 s22, 3072
	s_mov_b32 m0, s22
	s_nop 0
	global_load_lds_dwordx4 v[10:11], off
	s_add_i32 m0, s22, 1024
	s_nop 0
	global_load_lds_dwordx4 v[12:13], off
	s_add_i32 m0, s22, 2048
	s_nop 0
	global_load_lds_dwordx4 v[14:15], off
	v_lshl_add_u64 v[10:11], v[10:11], 0, s[12:13]
	v_lshl_add_u64 v[12:13], v[12:13], 0, s[12:13]
	v_lshl_add_u64 v[14:15], v[14:15], 0, s[12:13]
	s_mov_b32 s20, 0
	s_mov_b32 s5, 27
; __device__ __forceinline__ u32x4 pack8(f32x4 a, f32x4 b) { u32x4 w; w.x = cvt_pk_bf16(a[0], a[1]); w.y = cvt_pk_bf16(a[2], a[3]); w.z = cvt_pk_bf16(b[0], b[1]); w.w = cvt_pk_bf16(b[2], b[3]); return w; }
;     __device__ __forceinline__ void operator()(const f32x4 (&acc)[2][2][4][2], const pg8::Unit& u, int wr, int wc, int fr, int fq) const {
; #pragma unroll
;         for (int ai = 0; ai < 2; ++ai)
; #pragma unroll
;             for (int m = 0; m < 4; ++m) { const int row = u.pm * 256 + ai * 128 + wr * 64 + m * 16 + fr; float ss = 0.f;
;                 const float* xrow = row < MP ? xp + (size_t)row * D : xs + (size_t)(row - MP) * D;
; #pragma unroll
;                 for (int bj = 0; bj < 2; ++bj) { const int col = u.pn * 256 + bj * 128 + wc * 32 + 8 * fq;
;                     f32x4 v0 = acc[ai][bj][m][0] + *(const f32x4*)(xrow + col), v1 = acc[ai][bj][m][1] + *(const f32x4*)(xrow + col + 4);
;                     ss += (v0[0] * v0[0] + v0[1] * v0[1]) + (v0[2] * v0[2] + v0[3] * v0[3]) + (v1[0] * v1[0] + v1[1] * v1[1]) + (v1[2] * v1[2] + v1[3] * v1[3]);
;                     *(u32x4*)(X2B + (size_t)row * D + col) = pack8(v0, v1); }
;                 ss += __shfl_xor(ss, 16); ss += __shfl_xor(ss, 32);
;                 if (fq == 0) atomicAdd(rss + row, ss); }
;     }
.Lstrip_P4_k1:
	s_waitcnt vmcnt(12)
	v_add_u32_e32 v7, s20, v6
	ds_read_b128 v[24:27], v7
	ds_read_b128 v[28:31], v7 offset:1024
	ds_read_b128 v[32:35], v7 offset:2048
	s_add_i32 s22, s21, s20
	s_waitcnt lgkmcnt(0)
	s_mov_b32 m0, s22
	s_nop 0
	global_load_lds_dwordx4 v[10:11], off
	s_add_i32 m0, s22, 1024
	s_nop 0
	global_load_lds_dwordx4 v[12:13], off
	s_add_i32 m0, s22, 2048
	s_nop 0
	global_load_lds_dwordx4 v[14:15], off
	v_lshl_add_u64 v[10:11], v[10:11], 0, s[12:13]
	v_lshl_add_u64 v[12:13], v[12:13], 0, s[12:13]
	v_lshl_add_u64 v[14:15], v[14:15], 0, s[12:13]
	v_mfma_f32_16x16x32_bf16 v[16:19], v[28:31], v[24:27], v[16:19]
	v_mfma_f32_16x16x32_bf16 v[20:23], v[32:35], v[24:27], v[20:23]
	s_addk_i32 s20, 3072
	s_cmpk_eq_u32 s20, 15360
	s_cselect_b32 s20, 0, s20
	s_add_i32 s5, s5, -1
	s_cmp_lg_u32 s5, 0
	s_cbranch_scc1 .Lstrip_P4_k1
	s_waitcnt vmcnt(12)
	ds_read_b128 v[24:27], v6 offset:6144
	ds_read_b128 v[28:31], v6 offset:7168
	ds_read_b128 v[32:35], v6 offset:8192
	s_waitcnt lgkmcnt(0)
	v_mfma_f32_16x16x32_bf16 v[16:19], v[28:31], v[24:27], v[16:19]
	v_mfma_f32_16x16x32_bf16 v[20:23], v[32:35], v[24:27], v[20:23]
	s_waitcnt vmcnt(9)
	ds_read_b128 v[24:27], v6 offset:9216
	ds_read_b128 v[28:31], v6 offset:10240
	ds_read_b128 v[32:35], v6 offset:11264
	s_waitcnt lgkmcnt(0)
	v_mfma_f32_16x16x32_bf16 v[16:19], v[28:31], v[24:27], v[16:19]
	v_mfma_f32_16x16x32_bf16 v[20:23], v[32:35], v[24:27], v[20:23]
	s_waitcnt vmcnt(6)
	ds_read_b128 v[24:27], v6 offset:12288
	ds_read_b128 v[28:31], v6 offset:13312
	ds_read_b128 v[32:35], v6 offset:14336
	s_waitcnt lgkmcnt(0)
	v_mfma_f32_16x16x32_bf16 v[16:19], v[28:31], v[24:27], v[16:19]
	v_mfma_f32_16x16x32_bf16 v[20:23], v[32:35], v[24:27], v[20:23]
	s_waitcnt vmcnt(3)
	ds_read_b128 v[24:27], v6 offset:0
	ds_read_b128 v[28:31], v6 offset:1024
	ds_read_b128 v[32:35], v6 offset:2048
	s_waitcnt lgkmcnt(0)
	v_mfma_f32_16x16x32_bf16 v[16:19], v[28:31], v[24:27], v[16:19]
	v_mfma_f32_16x16x32_bf16 v[20:23], v[32:35], v[24:27], v[20:23]
	s_waitcnt vmcnt(0)
	ds_read_b128 v[24:27], v6 offset:3072
	ds_read_b128 v[28:31], v6 offset:4096
	ds_read_b128 v[32:35], v6 offset:5120
	s_waitcnt lgkmcnt(0)
	v_mfma_f32_16x16x32_bf16 v[16:19], v[28:31], v[24:27], v[16:19]
	v_mfma_f32_16x16x32_bf16 v[20:23], v[32:35], v[24:27], v[20:23]
	s_nop 7
	s_nop 1
	v_add_f32_e32 v16, v16, v120
	v_add_f32_e32 v17, v17, v121
	v_add_f32_e32 v18, v18, v122
	v_add_f32_e32 v19, v19, v123
	v_add_f32_e32 v20, v20, v124
	v_add_f32_e32 v21, v21, v125
	v_add_f32_e32 v22, v22, v126
	v_add_f32_e32 v23, v23, v127
	v_mul_f32_e32 v144, v16, v16
	v_fmac_f32_e32 v144, v17, v17
	v_fmac_f32_e32 v144, v18, v18
	v_fmac_f32_e32 v144, v19, v19
	v_fmac_f32_e32 v144, v20, v20
	v_fmac_f32_e32 v144, v21, v21
	v_fmac_f32_e32 v144, v22, v22
	v_fmac_f32_e32 v144, v23, v23
	v_cvt_pk_bf16_f32 v136, v16, v17
	v_cvt_pk_bf16_f32 v137, v18, v19
	v_cvt_pk_bf16_f32 v138, v20, v21
	v_cvt_pk_bf16_f32 v139, v22, v23
	s_add_u32 s22, s88, 0x18400000
	s_addc_u32 s23, s89, 0
	v_lshlrev_b32_e32 v0, 11, v5
	v_lshl_add_u32 v0, v2, 1, v0
	v_mov_b32_e32 v1, 0
	v_lshl_add_u64 v[0:1], s[22:23], 0, v[0:1]
	global_store_dwordx4 v[0:1], v[136:139], off
	v_lshlrev_b32_e32 v146, 2, v132
	v_xor_b32_e32 v145, 64, v146
	v_xor_b32_e32 v146, 0x80, v146
	ds_bpermute_b32 v147, v145, v144
	s_add_u32 s22, s88, 0x100000
	s_addc_u32 s23, s89, 0
	v_lshlrev_b32_e32 v0, 2, v5
	v_mov_b32_e32 v1, 0
	v_lshl_add_u64 v[0:1], s[22:23], 0, v[0:1]
	v_cmp_gt_u32_e32 vcc, 16, v132
	s_waitcnt lgkmcnt(0)
	v_add_f32_e32 v144, v144, v147
	ds_bpermute_b32 v147, v146, v144
	s_waitcnt lgkmcnt(0)
	v_add_f32_e32 v144, v144, v147
	s_and_saveexec_b64 s[22:23], vcc
	global_atomic_add_f32 v[0:1], v144, off
	s_or_b64 exec, exec, s[22:23]

;     __device__ __forceinline__ void operator()(const f32x4 (&acc)[2][2][4][2], const pg8::Unit& u, int wr, int wc, int fr, int fq) const {
;     ...
;             for (int m = 0; m < 4; ++m) { const int row = u.pm * 256 + ai * 128 + wr * 64 + m * 16 + fr; float ss = 0.f;
; #pragma unroll
;                 for (int bj = 0; bj < 2; ++bj) { const int col = u.pn * 256 + bj * 128 + wc * 32 + 8 * fq;
;                     f32x4 x0, x1; unpack_bf16x8(*(const u32x4*)(X2B + (size_t)row * D + col), x0, x1);
;                     const f32x4 v0 = acc[ai][bj][m][0] + x0, v1 = acc[ai][bj][m][1] + x1;
.LBB0_953:
	s_waitcnt vmcnt(0)
	v_readlane_b32 s46, v254, 22
	s_barrier
	s_and_b32 s0, s44, 7
	s_lshr_b32 s1, s44, 3
	s_and_b32 s1, s1, 7
	s_lshl_b32 s0, s0, 3
	s_add_i32 s0, s0, s1
	s_mulk_i32 s0, 0x110
	s_addk_i32 s0, 0x100
	s_lshr_b32 s1, s44, 6
	v_readlane_b32 s2, v254, 21
	s_nop 3
	s_lshl_b32 s3, s1, 8
	s_mul_i32 s21, s2, 15360
	s_lshl_b32 s2, s2, 5
	s_add_i32 s3, s3, s2
	s_mov_b32 s4, 0x1600
	s_add_u32 s8, s88, 0xb800000
	s_addc_u32 s9, s89, 0
	s_add_u32 s10, s88, 0x2700000
	s_addc_u32 s11, s89, 0
	s_mov_b64 s[6:7], 0x5800
	s_mov_b64 s[12:13], 64
	v_and_b32_e32 v8, 15, v132
	v_lshrrev_b32_e32 v9, 4, v132
	v_add_u32_e32 v5, s0, v8
	v_lshl_add_u32 v2, v9, 3, s3
	v_lshlrev_b32_e32 v6, 4, v9
	v_lshrrev_b32_e32 v7, 3, v8
	v_lshlrev_b32_e32 v7, 5, v7
	v_xor_b32_e32 v6, v6, v7
	v_lshl_add_u32 v6, v8, 6, v6
	v_add_u32_e32 v6, s21, v6
	v_lshrrev_b32_e32 v36, 2, v132
	v_and_b32_e32 v37, 3, v132
	v_lshrrev_b32_e32 v38, 5, v132
	v_lshlrev_b32_e32 v37, 4, v37
	v_lshlrev_b32_e32 v38, 5, v38
	v_xor_b32_e32 v37, v37, v38
	v_add_u32_e32 v38, s0, v36
	v_lshrrev_b32_e32 v39, 2, v36
	v_and_b32_e32 v40, 3, v36
	v_lshl_add_u32 v39, v39, 3, v40
	v_add_u32_e32 v39, s3, v39
	v_mul_lo_u32 v10, v38, s4
	v_mul_lo_u32 v12, v39, s4
	v_mov_b32_e32 v11, 0
	v_mov_b32_e32 v13, 0
	v_add_u32_e32 v10, v10, v37
	v_add_u32_e32 v12, v12, v37
	v_lshl_add_u64 v[10:11], s[8:9], 0, v[10:11]
	v_lshl_add_u64 v[12:13], s[10:11], 0, v[12:13]
	v_lshl_add_u64 v[14:15], v[12:13], 0, s[6:7]
	s_add_u32 s22, s88, 0x18400000
	s_addc_u32 s23, s89, 0
	v_lshlrev_b32_e32 v0, 11, v5
	v_lshl_add_u32 v0, v2, 1, v0
	v_mov_b32_e32 v1, 0
	v_lshl_add_u64 v[0:1], s[22:23], 0, v[0:1]
	global_load_dwordx4 v[120:123], v[0:1], off
	v_mov_b32_e32 v16, 0
	v_mov_b32_e32 v17, 0
	v_mov_b32_e32 v18, 0
	v_mov_b32_e32 v19, 0
	v_mov_b32_e32 v20, 0
	v_mov_b32_e32 v21, 0
	v_mov_b32_e32 v22, 0
	v_mov_b32_e32 v23, 0
	s_mov_b32 s22, s21
	s_mov_b32 m0, s22
	s_nop 0
	global_load_lds_dwordx4 v[10:11], off
	s_add_i32 m0, s22, 1024
	s_nop 0
	global_load_lds_dwordx4 v[12:13], off
	s_add_i32 m0, s22, 2048
	s_nop 0
	global_load_lds_dwordx4 v[14:15], off
	v_lshl_add_u64 v[10:11], v[10:11], 0, s[12:13]
	v_lshl_add_u64 v[12:13], v[12:13], 0, s[12:13]
	v_lshl_add_u64 v[14:15], v[14:15], 0, s[12:13]
	s_addk_i32 s22, 3072
	s_mov_b32 m0, s22
	s_nop 0
	global_load_lds_dwordx4 v[10:11], off
	s_add_i32 m0, s22, 1024
	s_nop 0
	global_load_lds_dwordx4 v[12:13], off
	s_add_i32 m0, s22, 2048
	s_nop 0
	global_load_lds_dwordx4 v[14:15], off
	v_lshl_add_u64 v[10:11], v[10:11], 0, s[12:13]
	v_lshl_add_u64 v[12:13], v[12:13], 0, s[12:13]
	v_lshl_add_u64 v[14:15], v[14:15], 0, s[12:13]
	s_addk_i32 s22, 3072
	s_mov_b32 m0, s22
	s_nop 0
	global_load_lds_dwordx4 v[10:11], off
	s_add_i32 m0, s22, 1024
	s_nop 0
	global_load_lds_dwordx4 v[12:13], off
	s_add_i32 m0, s22, 2048
	s_nop 0
	global_load_lds_dwordx4 v[14:15], off
	v_lshl_add_u64 v[10:11], v[10:11], 0, s[12:13]
	v_lshl_add_u64 v[12:13], v[12:13], 0, s[12:13]
	v_lshl_add_u64 v[14:15], v[14:15], 0, s[12:13]
	s_addk_i32 s22, 3072
	s_mov_b32 m0, s22
	s_nop 0
	global_load_lds_dwordx4 v[10:11], off
	s_add_i32 m0, s22, 1024
	s_nop 0
	global_load_lds_dwordx4 v[12:13], off
	s_add_i32 m0, s22, 2048
	s_nop 0
	global_load_lds_dwordx4 v[14:15], off
	v_lshl_add_u64 v[10:11], v[10:11], 0, s[12:13]
	v_lshl_add_u64 v[12:13], v[12:13], 0, s[12:13]
	v_lshl_add_u64 v[14:15], v[14:15], 0, s[12:13]
	s_addk_i32 s22, 3072
	s_mov_b32 m0, s22
	s_nop 0
	global_load_lds_dwordx4 v[10:11], off
	s_add_i32 m0, s22, 1024
	s_nop 0
	global_load_lds_dwordx4 v[12:13], off
	s_add_i32 m0, s22, 2048
	s_nop 0
	global_load_lds_dwordx4 v[14:15], off
	v_lshl_add_u64 v[10:11], v[10:11], 0, s[12:13]
	v_lshl_add_u64 v[12:13], v[12:13], 0, s[12:13]
	v_lshl_add_u64 v[14:15], v[14:15], 0, s[12:13]
	s_mov_b32 s20, 0
	s_mov_b32 s5, 83
; __device__ __forceinline__ u32x4 pack8(f32x4 a, f32x4 b) { u32x4 w; w.x = cvt_pk_bf16(a[0], a[1]); w.y = cvt_pk_bf16(a[2], a[3]); w.z = cvt_pk_bf16(b[0], b[1]); w.w = cvt_pk_bf16(b[2], b[3]); return w; }
;     __device__ __forceinline__ void operator()(const f32x4 (&acc)[2][2][4][2], const pg8::Unit& u, int wr, int wc, int fr, int fq) const {
;     ...
;             for (int m = 0; m < 4; ++m) { const int row = u.pm * 256 + ai * 128 + wr * 64 + m * 16 + fr; float ss = 0.f;
; #pragma unroll
;                 for (int bj = 0; bj < 2; ++bj) { const int col = u.pn * 256 + bj * 128 + wc * 32 + 8 * fq;
;                     f32x4 x0, x1; unpack_bf16x8(*(const u32x4*)(X2B + (size_t)row * D + col), x0, x1);
;                     const f32x4 v0 = acc[ai][bj][m][0] + x0, v1 = acc[ai][bj][m][1] + x1;
;                     ss += (v0[0] * v0[0] + v0[1] * v0[1]) + (v0[2] * v0[2] + v0[3] * v0[3]) + (v1[0] * v1[0] + v1[1] * v1[1]) + (v1[2] * v1[2] + v1[3] * v1[3]);
;                     *(u32x4*)(X3B + (size_t)row * D + col) = pack8(v0, v1); }
;                 ss += __shfl_xor(ss, 16); ss += __shfl_xor(ss, 32);
;                 if (fq == 0) atomicAdd(rss + row, ss); }
.Lstrip_P6_k1:
	s_waitcnt vmcnt(12)
	v_add_u32_e32 v7, s20, v6
	ds_read_b128 v[24:27], v7
	ds_read_b128 v[28:31], v7 offset:1024
	ds_read_b128 v[32:35], v7 offset:2048
	s_add_i32 s22, s21, s20
	s_waitcnt lgkmcnt(0)
	s_mov_b32 m0, s22
	s_nop 0
	global_load_lds_dwordx4 v[10:11], off
	s_add_i32 m0, s22, 1024
	s_nop 0
	global_load_lds_dwordx4 v[12:13], off
	s_add_i32 m0, s22, 2048
	s_nop 0
	global_load_lds_dwordx4 v[14:15], off
	v_lshl_add_u64 v[10:11], v[10:11], 0, s[12:13]
	v_lshl_add_u64 v[12:13], v[12:13], 0, s[12:13]
	v_lshl_add_u64 v[14:15], v[14:15], 0, s[12:13]
	v_mfma_f32_16x16x32_bf16 v[16:19], v[28:31], v[24:27], v[16:19]
	v_mfma_f32_16x16x32_bf16 v[20:23], v[32:35], v[24:27], v[20:23]
	s_addk_i32 s20, 3072
	s_cmpk_eq_u32 s20, 15360
	s_cselect_b32 s20, 0, s20
	s_add_i32 s5, s5, -1
	s_cmp_lg_u32 s5, 0
	s_cbranch_scc1 .Lstrip_P6_k1
	s_waitcnt vmcnt(12)
	ds_read_b128 v[24:27], v6 offset:9216
	ds_read_b128 v[28:31], v6 offset:10240
	ds_read_b128 v[32:35], v6 offset:11264
	s_waitcnt lgkmcnt(0)
	v_mfma_f32_16x16x32_bf16 v[16:19], v[28:31], v[24:27], v[16:19]
	v_mfma_f32_16x16x32_bf16 v[20:23], v[32:35], v[24:27], v[20:23]
	s_waitcnt vmcnt(9)
	ds_read_b128 v[24:27], v6 offset:12288
	ds_read_b128 v[28:31], v6 offset:13312
	ds_read_b128 v[32:35], v6 offset:14336
	s_waitcnt lgkmcnt(0)
	v_mfma_f32_16x16x32_bf16 v[16:19], v[28:31], v[24:27], v[16:19]
	v_mfma_f32_16x16x32_bf16 v[20:23], v[32:35], v[24:27], v[20:23]
	s_waitcnt vmcnt(6)
	ds_read_b128 v[24:27], v6 offset:0
	ds_read_b128 v[28:31], v6 offset:1024
	ds_read_b128 v[32:35], v6 offset:2048
	s_waitcnt lgkmcnt(0)
	v_mfma_f32_16x16x32_bf16 v[16:19], v[28:31], v[24:27], v[16:19]
	v_mfma_f32_16x16x32_bf16 v[20:23], v[32:35], v[24:27], v[20:23]
	s_waitcnt vmcnt(3)
	ds_read_b128 v[24:27], v6 offset:3072
	ds_read_b128 v[28:31], v6 offset:4096
	ds_read_b128 v[32:35], v6 offset:5120
	s_waitcnt lgkmcnt(0)
	v_mfma_f32_16x16x32_bf16 v[16:19], v[28:31], v[24:27], v[16:19]
	v_mfma_f32_16x16x32_bf16 v[20:23], v[32:35], v[24:27], v[20:23]
	s_waitcnt vmcnt(0)
	ds_read_b128 v[24:27], v6 offset:6144
	ds_read_b128 v[28:31], v6 offset:7168
	ds_read_b128 v[32:35], v6 offset:8192
	s_waitcnt lgkmcnt(0)
	v_mfma_f32_16x16x32_bf16 v[16:19], v[28:31], v[24:27], v[16:19]
	v_mfma_f32_16x16x32_bf16 v[20:23], v[32:35], v[24:27], v[20:23]
	s_nop 7
	s_nop 1
	v_lshlrev_b32_e32 v136, 16, v120
	v_and_b32_e32 v137, 0xffff0000, v120
	v_lshlrev_b32_e32 v138, 16, v121
	v_and_b32_e32 v139, 0xffff0000, v121
	v_lshlrev_b32_e32 v140, 16, v122
	v_and_b32_e32 v141, 0xffff0000, v122
	v_lshlrev_b32_e32 v142, 16, v123
	v_and_b32_e32 v143, 0xffff0000, v123
	v_add_f32_e32 v16, v16, v136
	v_add_f32_e32 v17, v17, v137
	v_add_f32_e32 v18, v18, v138
	v_add_f32_e32 v19, v19, v139
	v_add_f32_e32 v20, v20, v140
	v_add_f32_e32 v21, v21, v141
	v_add_f32_e32 v22, v22, v142
	v_add_f32_e32 v23, v23, v143
	v_mul_f32_e32 v144, v16, v16
	v_fmac_f32_e32 v144, v17, v17
	v_fmac_f32_e32 v144, v18, v18
	v_fmac_f32_e32 v144, v19, v19
	v_fmac_f32_e32 v144, v20, v20
	v_fmac_f32_e32 v144, v21, v21
	v_fmac_f32_e32 v144, v22, v22
	v_fmac_f32_e32 v144, v23, v23
	v_cvt_pk_bf16_f32 v136, v16, v17
	v_cvt_pk_bf16_f32 v137, v18, v19
	v_cvt_pk_bf16_f32 v138, v20, v21
	v_cvt_pk_bf16_f32 v139, v22, v23
	s_add_u32 s22, s88, 0x9600000
	s_addc_u32 s23, s89, 0
	v_lshlrev_b32_e32 v0, 11, v5
	v_lshl_add_u32 v0, v2, 1, v0
	v_mov_b32_e32 v1, 0
	v_lshl_add_u64 v[0:1], s[22:23], 0, v[0:1]
	global_store_dwordx4 v[0:1], v[136:139], off
	v_lshlrev_b32_e32 v146, 2, v132
	v_xor_b32_e32 v145, 64, v146
	v_xor_b32_e32 v146, 0x80, v146
	ds_bpermute_b32 v147, v145, v144
	s_add_u32 s22, s88, 0x120000
	s_addc_u32 s23, s89, 0
	v_lshlrev_b32_e32 v0, 2, v5
	v_mov_b32_e32 v1, 0
	v_lshl_add_u64 v[0:1], s[22:23], 0, v[0:1]
	v_cmp_gt_u32_e32 vcc, 16, v132
	s_waitcnt lgkmcnt(0)
	v_add_f32_e32 v144, v144, v147
	ds_bpermute_b32 v147, v146, v144
	s_waitcnt lgkmcnt(0)
	v_add_f32_e32 v144, v144, v147
	s_and_saveexec_b64 s[22:23], vcc
	global_atomic_add_f32 v[0:1], v144, off
	s_or_b64 exec, exec, s[22:23]
